# gla_prep q~/k~ row stores marked nt (whole-line streaming outputs)
# baseline (speedup 1.0000x reference)
; DEVINL u16 f2bf(float a) { return (u16)(pk2(a, 0.f) & 0xffffu); }
; DEVINL float bf2f(u16 h) { return __uint_as_float(((unsigned)h) << 16); }
; DEVINL int fragpos(int idx) { const int w = idx & 31; return (idx & ~31) + (((w & 15) >> 2) << 3) + (w & 3) + ((w >> 4) << 2); }
; DEVINL void gla_prep_unit(const Params& p, int unit) {
;     ...
;     const float bedge = run;
;     const long hb = ((long)(dir * 2 + b) * 4 + h);
;     const int pk = fragpos(kk);
;     u16* qt = (u16*)(ws + O_QT) + (hb * 4096 + c * 64) * 128 + pk;
;     u16* kt = (u16*)(ws + O_KT) + (hb * 4096 + c * 64) * 128 + pk;
;     ((float*)(ws + O_DEC))[(hb * 64 + c) * 128 + kk] = __expf(bedge);
;     u16* KDr = KD + (dir * 128 + kk) * 72;
;     const unsigned short* qsrc = cols + tok0 * NCP + C_Q + h * 128 + kk;
;     const unsigned short* ksrc = cols + tok0 * NCP + C_K + h * 128 + kk;
; #pragma unroll 1
;     for (int i0 = 0; i0 < 64; i0 += 8) {
;       u16 qv[8], kv[8];
; #pragma unroll
;       for (int j = 0; j < 8; ++j) { qv[j] = qsrc[(long)(i0 + j) * NCP]; kv[j] = ksrc[(long)(i0 + j) * NCP]; }
; #pragma unroll
;       for (int j = 0; j < 8; ++j) {
;         const int i = i0 + j;
;         float bb = Gc[i * 128];
;         float q = bf2f(qv[j]);
;         float k = bf2f(kv[j]);
;         qt[i * 128] = f2bf(q * 0.08838834764831845f * __expf(bb));
;         kt[i * 128] = f2bf(k * __expf(-bb));
;         KDr[fragpos(i)] = f2bf(k * __expf(bedge - bb));
;       }
;     }
.Lgl_nodec:
	s_waitcnt lgkmcnt(0)
	s_barrier
	s_mov_b32 s56, 0x3db504f3
	ds_read_b128 v[116:119], v22 offset:0
	ds_read_b128 v[120:123], v22 offset:64
	ds_read_b64 v[124:125], v23 offset:0
	ds_read_b64 v[126:127], v23 offset:32
	s_waitcnt lgkmcnt(0)
	v_lshlrev_b32_e32 v128, 16, v124
	v_and_b32_e32 v129, 0xffff0000, v124
	v_lshlrev_b32_e32 v130, 16, v125
	v_and_b32_e32 v131, 0xffff0000, v125
	v_lshlrev_b32_e32 v132, 16, v126
	v_and_b32_e32 v133, 0xffff0000, v126
	v_lshlrev_b32_e32 v134, 16, v127
	v_and_b32_e32 v135, 0xffff0000, v127
	v_mul_f32_e32 v116, 0x3fb8aa3b, v116
	v_exp_f32_e32 v116, v116
	v_mul_f32_e32 v128, s56, v128
	v_mul_f32_e32 v128, v128, v116
	v_mul_f32_e32 v117, 0x3fb8aa3b, v117
	v_exp_f32_e32 v117, v117
	v_mul_f32_e32 v129, s56, v129
	v_mul_f32_e32 v129, v129, v117
	v_mul_f32_e32 v118, 0x3fb8aa3b, v118
	v_exp_f32_e32 v118, v118
	v_mul_f32_e32 v130, s56, v130
	v_mul_f32_e32 v130, v130, v118
	v_mul_f32_e32 v119, 0x3fb8aa3b, v119
	v_exp_f32_e32 v119, v119
	v_mul_f32_e32 v131, s56, v131
	v_mul_f32_e32 v131, v131, v119
	v_mul_f32_e32 v120, 0x3fb8aa3b, v120
	v_exp_f32_e32 v120, v120
	v_mul_f32_e32 v132, s56, v132
	v_mul_f32_e32 v132, v132, v120
	v_mul_f32_e32 v121, 0x3fb8aa3b, v121
	v_exp_f32_e32 v121, v121
	v_mul_f32_e32 v133, s56, v133
	v_mul_f32_e32 v133, v133, v121
	v_mul_f32_e32 v122, 0x3fb8aa3b, v122
	v_exp_f32_e32 v122, v122
	v_mul_f32_e32 v134, s56, v134
	v_mul_f32_e32 v134, v134, v122
	v_mul_f32_e32 v123, 0x3fb8aa3b, v123
	v_exp_f32_e32 v123, v123
	v_mul_f32_e32 v135, s56, v135
	v_mul_f32_e32 v135, v135, v123
	v_cvt_pk_bf16_f32 v140, v128, v129
	v_cvt_pk_bf16_f32 v141, v130, v131
	v_cvt_pk_bf16_f32 v142, v132, v133
	v_cvt_pk_bf16_f32 v143, v134, v135
	s_lshl_b32 s48, s43, 2
	s_add_u32 s48, s48, 0
	s_add_u32 s48, s48, s41
	s_lshl_b32 s48, s48, 20
	s_lshl_b32 s57, s42, 14
	s_add_u32 s48, s48, s57
	s_add_u32 s48, s48, 0
	s_add_u32 s58, s92, s48
	s_addc_u32 s59, s93, 0
	s_add_u32 s58, s58, 0x17400000
	s_addc_u32 s59, s59, 0
	global_store_dwordx4 v2, v[140:143], s[58:59] nt
	ds_read_b128 v[116:119], v22 offset:16384
	ds_read_b128 v[120:123], v22 offset:16448
	ds_read_b64 v[124:125], v23 offset:8192
	ds_read_b64 v[126:127], v23 offset:8224
	s_waitcnt lgkmcnt(0)
	v_lshlrev_b32_e32 v128, 16, v124
	v_and_b32_e32 v129, 0xffff0000, v124
	v_lshlrev_b32_e32 v130, 16, v125
	v_and_b32_e32 v131, 0xffff0000, v125
	v_lshlrev_b32_e32 v132, 16, v126
	v_and_b32_e32 v133, 0xffff0000, v126
	v_lshlrev_b32_e32 v134, 16, v127
	v_and_b32_e32 v135, 0xffff0000, v127
	v_mul_f32_e32 v116, 0x3fb8aa3b, v116
	v_exp_f32_e32 v116, v116
	v_mul_f32_e32 v128, s56, v128
	v_mul_f32_e32 v128, v128, v116
	v_mul_f32_e32 v117, 0x3fb8aa3b, v117
	v_exp_f32_e32 v117, v117
	v_mul_f32_e32 v129, s56, v129
	v_mul_f32_e32 v129, v129, v117
	v_mul_f32_e32 v118, 0x3fb8aa3b, v118
	v_exp_f32_e32 v118, v118
	v_mul_f32_e32 v130, s56, v130
	v_mul_f32_e32 v130, v130, v118
	v_mul_f32_e32 v119, 0x3fb8aa3b, v119
	v_exp_f32_e32 v119, v119
	v_mul_f32_e32 v131, s56, v131
	v_mul_f32_e32 v131, v131, v119
	v_mul_f32_e32 v120, 0x3fb8aa3b, v120
	v_exp_f32_e32 v120, v120
	v_mul_f32_e32 v132, s56, v132
	v_mul_f32_e32 v132, v132, v120
	v_mul_f32_e32 v121, 0x3fb8aa3b, v121
	v_exp_f32_e32 v121, v121
	v_mul_f32_e32 v133, s56, v133
	v_mul_f32_e32 v133, v133, v121
	v_mul_f32_e32 v122, 0x3fb8aa3b, v122
	v_exp_f32_e32 v122, v122
	v_mul_f32_e32 v134, s56, v134
	v_mul_f32_e32 v134, v134, v122
	v_mul_f32_e32 v123, 0x3fb8aa3b, v123
	v_exp_f32_e32 v123, v123
	v_mul_f32_e32 v135, s56, v135
	v_mul_f32_e32 v135, v135, v123
	v_cvt_pk_bf16_f32 v140, v128, v129
	v_cvt_pk_bf16_f32 v141, v130, v131
	v_cvt_pk_bf16_f32 v142, v132, v133
	v_cvt_pk_bf16_f32 v143, v134, v135
	s_lshl_b32 s48, s43, 2
	s_add_u32 s48, s48, 0
	s_add_u32 s48, s48, s41
	s_lshl_b32 s48, s48, 20
	s_lshl_b32 s57, s42, 14
	s_add_u32 s48, s48, s57
	s_add_u32 s48, s48, 8192
	s_add_u32 s58, s92, s48
	s_addc_u32 s59, s93, 0
	s_add_u32 s58, s58, 0x17400000
	s_addc_u32 s59, s59, 0
	global_store_dwordx4 v2, v[140:143], s[58:59] nt
	ds_read_b128 v[116:119], v22 offset:0
	ds_read_b128 v[120:123], v22 offset:64
	ds_read_b64 v[124:125], v23 offset:16384
	ds_read_b64 v[126:127], v23 offset:16416
	s_waitcnt lgkmcnt(0)
	v_lshlrev_b32_e32 v128, 16, v124
	v_and_b32_e32 v129, 0xffff0000, v124
	v_lshlrev_b32_e32 v130, 16, v125
	v_and_b32_e32 v131, 0xffff0000, v125
	v_lshlrev_b32_e32 v132, 16, v126
	v_and_b32_e32 v133, 0xffff0000, v126
	v_lshlrev_b32_e32 v134, 16, v127
	v_and_b32_e32 v135, 0xffff0000, v127
	v_mul_f32_e32 v116, 0xbfb8aa3b, v116
	v_exp_f32_e32 v116, v116
	s_nop 0
	v_mul_f32_e32 v128, v116, v128
	v_mul_f32_e32 v117, 0xbfb8aa3b, v117
	v_exp_f32_e32 v117, v117
	s_nop 0
	v_mul_f32_e32 v129, v117, v129
	v_mul_f32_e32 v118, 0xbfb8aa3b, v118
	v_exp_f32_e32 v118, v118
	s_nop 0
	v_mul_f32_e32 v130, v118, v130
	v_mul_f32_e32 v119, 0xbfb8aa3b, v119
	v_exp_f32_e32 v119, v119
	s_nop 0
	v_mul_f32_e32 v131, v119, v131
	v_mul_f32_e32 v120, 0xbfb8aa3b, v120
	v_exp_f32_e32 v120, v120
	s_nop 0
	v_mul_f32_e32 v132, v120, v132
	v_mul_f32_e32 v121, 0xbfb8aa3b, v121
	v_exp_f32_e32 v121, v121
	s_nop 0
	v_mul_f32_e32 v133, v121, v133
	v_mul_f32_e32 v122, 0xbfb8aa3b, v122
	v_exp_f32_e32 v122, v122
	s_nop 0
	v_mul_f32_e32 v134, v122, v134
	v_mul_f32_e32 v123, 0xbfb8aa3b, v123
	v_exp_f32_e32 v123, v123
	s_nop 0
	v_mul_f32_e32 v135, v123, v135
	v_cvt_pk_bf16_f32 v140, v128, v129
	v_cvt_pk_bf16_f32 v141, v130, v131
	v_cvt_pk_bf16_f32 v142, v132, v133
	v_cvt_pk_bf16_f32 v143, v134, v135
	s_lshl_b32 s48, s43, 2
	s_add_u32 s48, s48, 0
	s_add_u32 s48, s48, s41
	s_lshl_b32 s48, s48, 20
	s_lshl_b32 s57, s42, 14
	s_add_u32 s48, s48, s57
	s_add_u32 s48, s48, 0
	s_add_u32 s58, s92, s48
	s_addc_u32 s59, s93, 0
	s_add_u32 s58, s58, 0x18400000
	s_addc_u32 s59, s59, 0
	global_store_dwordx4 v2, v[140:143], s[58:59] nt
	ds_read_b128 v[116:119], v22 offset:16384
	ds_read_b128 v[120:123], v22 offset:16448
	ds_read_b64 v[124:125], v23 offset:24576
	ds_read_b64 v[126:127], v23 offset:24608
	s_waitcnt lgkmcnt(0)
; DEVINL u16 f2bf(float a) { return (u16)(pk2(a, 0.f) & 0xffffu); }
; DEVINL float bf2f(u16 h) { return __uint_as_float(((unsigned)h) << 16); }
; DEVINL int fragpos(int idx) { const int w = idx & 31; return (idx & ~31) + (((w & 15) >> 2) << 3) + (w & 3) + ((w >> 4) << 2); }
; DEVINL void gla_prep_unit(const Params& p, int unit) {
;     ...
;     const float bedge = run;
;     const long hb = ((long)(dir * 2 + b) * 4 + h);
;     const int pk = fragpos(kk);
;     u16* qt = (u16*)(ws + O_QT) + (hb * 4096 + c * 64) * 128 + pk;
;     u16* kt = (u16*)(ws + O_KT) + (hb * 4096 + c * 64) * 128 + pk;
;     ((float*)(ws + O_DEC))[(hb * 64 + c) * 128 + kk] = __expf(bedge);
;     u16* KDr = KD + (dir * 128 + kk) * 72;
;     const unsigned short* qsrc = cols + tok0 * NCP + C_Q + h * 128 + kk;
;     const unsigned short* ksrc = cols + tok0 * NCP + C_K + h * 128 + kk;
; #pragma unroll 1
;     for (int i0 = 0; i0 < 64; i0 += 8) {
;       u16 qv[8], kv[8];
; #pragma unroll
;       for (int j = 0; j < 8; ++j) { qv[j] = qsrc[(long)(i0 + j) * NCP]; kv[j] = ksrc[(long)(i0 + j) * NCP]; }
; #pragma unroll
;       for (int j = 0; j < 8; ++j) {
;         const int i = i0 + j;
;         float bb = Gc[i * 128];
;         float q = bf2f(qv[j]);
;         float k = bf2f(kv[j]);
;         qt[i * 128] = f2bf(q * 0.08838834764831845f * __expf(bb));
;         kt[i * 128] = f2bf(k * __expf(-bb));
;         KDr[fragpos(i)] = f2bf(k * __expf(bedge - bb));
;       }
;     }
	v_lshlrev_b32_e32 v128, 16, v124
	v_and_b32_e32 v129, 0xffff0000, v124
	v_lshlrev_b32_e32 v130, 16, v125
	v_and_b32_e32 v131, 0xffff0000, v125
	v_lshlrev_b32_e32 v132, 16, v126
	v_and_b32_e32 v133, 0xffff0000, v126
	v_lshlrev_b32_e32 v134, 16, v127
	v_and_b32_e32 v135, 0xffff0000, v127
	v_mul_f32_e32 v116, 0xbfb8aa3b, v116
	v_exp_f32_e32 v116, v116
	s_nop 0
	v_mul_f32_e32 v128, v116, v128
	v_mul_f32_e32 v117, 0xbfb8aa3b, v117
	v_exp_f32_e32 v117, v117
	s_nop 0
	v_mul_f32_e32 v129, v117, v129
	v_mul_f32_e32 v118, 0xbfb8aa3b, v118
	v_exp_f32_e32 v118, v118
	s_nop 0
	v_mul_f32_e32 v130, v118, v130
	v_mul_f32_e32 v119, 0xbfb8aa3b, v119
	v_exp_f32_e32 v119, v119
	s_nop 0
	v_mul_f32_e32 v131, v119, v131
	v_mul_f32_e32 v120, 0xbfb8aa3b, v120
	v_exp_f32_e32 v120, v120
	s_nop 0
	v_mul_f32_e32 v132, v120, v132
	v_mul_f32_e32 v121, 0xbfb8aa3b, v121
	v_exp_f32_e32 v121, v121
	s_nop 0
	v_mul_f32_e32 v133, v121, v133
	v_mul_f32_e32 v122, 0xbfb8aa3b, v122
	v_exp_f32_e32 v122, v122
	s_nop 0
	v_mul_f32_e32 v134, v122, v134
	v_mul_f32_e32 v123, 0xbfb8aa3b, v123
	v_exp_f32_e32 v123, v123
	s_nop 0
	v_mul_f32_e32 v135, v123, v135
	v_cvt_pk_bf16_f32 v140, v128, v129
	v_cvt_pk_bf16_f32 v141, v130, v131
	v_cvt_pk_bf16_f32 v142, v132, v133
	v_cvt_pk_bf16_f32 v143, v134, v135
	s_lshl_b32 s48, s43, 2
	s_add_u32 s48, s48, 0
	s_add_u32 s48, s48, s41
	s_lshl_b32 s48, s48, 20
	s_lshl_b32 s57, s42, 14
	s_add_u32 s48, s48, s57
	s_add_u32 s48, s48, 8192
	s_add_u32 s58, s92, s48
	s_addc_u32 s59, s93, 0
	s_add_u32 s58, s58, 0x18400000
	s_addc_u32 s59, s59, 0
	global_store_dwordx4 v2, v[140:143], s[58:59] nt
	ds_read_b128 v[116:119], v22 offset:32768
	ds_read_b128 v[120:123], v22 offset:32832
	ds_read_b64 v[124:125], v23 offset:0
	ds_read_b64 v[126:127], v23 offset:32
	s_waitcnt lgkmcnt(0)
	v_lshlrev_b32_e32 v128, 16, v124
	v_and_b32_e32 v129, 0xffff0000, v124
	v_lshlrev_b32_e32 v130, 16, v125
	v_and_b32_e32 v131, 0xffff0000, v125
	v_lshlrev_b32_e32 v132, 16, v126
	v_and_b32_e32 v133, 0xffff0000, v126
	v_lshlrev_b32_e32 v134, 16, v127
	v_and_b32_e32 v135, 0xffff0000, v127
	v_mul_f32_e32 v116, 0x3fb8aa3b, v116
	v_exp_f32_e32 v116, v116
	v_mul_f32_e32 v128, s56, v128
	v_mul_f32_e32 v128, v128, v116
	v_mul_f32_e32 v117, 0x3fb8aa3b, v117
	v_exp_f32_e32 v117, v117
	v_mul_f32_e32 v129, s56, v129
	v_mul_f32_e32 v129, v129, v117
	v_mul_f32_e32 v118, 0x3fb8aa3b, v118
	v_exp_f32_e32 v118, v118
	v_mul_f32_e32 v130, s56, v130
	v_mul_f32_e32 v130, v130, v118
	v_mul_f32_e32 v119, 0x3fb8aa3b, v119
	v_exp_f32_e32 v119, v119
	v_mul_f32_e32 v131, s56, v131
	v_mul_f32_e32 v131, v131, v119
	v_mul_f32_e32 v120, 0x3fb8aa3b, v120
	v_exp_f32_e32 v120, v120
	v_mul_f32_e32 v132, s56, v132
	v_mul_f32_e32 v132, v132, v120
	v_mul_f32_e32 v121, 0x3fb8aa3b, v121
	v_exp_f32_e32 v121, v121
	v_mul_f32_e32 v133, s56, v133
	v_mul_f32_e32 v133, v133, v121
	v_mul_f32_e32 v122, 0x3fb8aa3b, v122
	v_exp_f32_e32 v122, v122
	v_mul_f32_e32 v134, s56, v134
	v_mul_f32_e32 v134, v134, v122
	v_mul_f32_e32 v123, 0x3fb8aa3b, v123
	v_exp_f32_e32 v123, v123
	v_mul_f32_e32 v135, s56, v135
	v_mul_f32_e32 v135, v135, v123
	v_cvt_pk_bf16_f32 v140, v128, v129
	v_cvt_pk_bf16_f32 v141, v130, v131
	v_cvt_pk_bf16_f32 v142, v132, v133
	v_cvt_pk_bf16_f32 v143, v134, v135
	s_lshl_b32 s48, s43, 2
	s_add_u32 s48, s48, 8
	s_add_u32 s48, s48, s41
	s_lshl_b32 s48, s48, 20
	s_lshl_b32 s57, s42, 14
	s_add_u32 s48, s48, s57
	s_add_u32 s48, s48, 0
	s_add_u32 s58, s92, s48
	s_addc_u32 s59, s93, 0
	s_add_u32 s58, s58, 0x17400000
	s_addc_u32 s59, s59, 0
	global_store_dwordx4 v2, v[140:143], s[58:59] nt
	ds_read_b128 v[116:119], v22 offset:49152
	ds_read_b128 v[120:123], v22 offset:49216
	ds_read_b64 v[124:125], v23 offset:8192
	ds_read_b64 v[126:127], v23 offset:8224
	s_waitcnt lgkmcnt(0)
; DEVINL u16 f2bf(float a) { return (u16)(pk2(a, 0.f) & 0xffffu); }
; DEVINL float bf2f(u16 h) { return __uint_as_float(((unsigned)h) << 16); }
; DEVINL int fragpos(int idx) { const int w = idx & 31; return (idx & ~31) + (((w & 15) >> 2) << 3) + (w & 3) + ((w >> 4) << 2); }
; DEVINL void gla_prep_unit(const Params& p, int unit) {
;     ...
;     const float bedge = run;
;     const long hb = ((long)(dir * 2 + b) * 4 + h);
;     const int pk = fragpos(kk);
;     u16* qt = (u16*)(ws + O_QT) + (hb * 4096 + c * 64) * 128 + pk;
;     u16* kt = (u16*)(ws + O_KT) + (hb * 4096 + c * 64) * 128 + pk;
;     ((float*)(ws + O_DEC))[(hb * 64 + c) * 128 + kk] = __expf(bedge);
;     u16* KDr = KD + (dir * 128 + kk) * 72;
;     const unsigned short* qsrc = cols + tok0 * NCP + C_Q + h * 128 + kk;
;     const unsigned short* ksrc = cols + tok0 * NCP + C_K + h * 128 + kk;
; #pragma unroll 1
;     for (int i0 = 0; i0 < 64; i0 += 8) {
;       u16 qv[8], kv[8];
; #pragma unroll
;       for (int j = 0; j < 8; ++j) { qv[j] = qsrc[(long)(i0 + j) * NCP]; kv[j] = ksrc[(long)(i0 + j) * NCP]; }
; #pragma unroll
;       for (int j = 0; j < 8; ++j) {
;         const int i = i0 + j;
;         float bb = Gc[i * 128];
;         float q = bf2f(qv[j]);
;         float k = bf2f(kv[j]);
;         qt[i * 128] = f2bf(q * 0.08838834764831845f * __expf(bb));
;         kt[i * 128] = f2bf(k * __expf(-bb));
;         KDr[fragpos(i)] = f2bf(k * __expf(bedge - bb));
;       }
;     }
	v_lshlrev_b32_e32 v128, 16, v124
	v_and_b32_e32 v129, 0xffff0000, v124
	v_lshlrev_b32_e32 v130, 16, v125
	v_and_b32_e32 v131, 0xffff0000, v125
	v_lshlrev_b32_e32 v132, 16, v126
	v_and_b32_e32 v133, 0xffff0000, v126
	v_lshlrev_b32_e32 v134, 16, v127
	v_and_b32_e32 v135, 0xffff0000, v127
	v_mul_f32_e32 v116, 0x3fb8aa3b, v116
	v_exp_f32_e32 v116, v116
	v_mul_f32_e32 v128, s56, v128
	v_mul_f32_e32 v128, v128, v116
	v_mul_f32_e32 v117, 0x3fb8aa3b, v117
	v_exp_f32_e32 v117, v117
	v_mul_f32_e32 v129, s56, v129
	v_mul_f32_e32 v129, v129, v117
	v_mul_f32_e32 v118, 0x3fb8aa3b, v118
	v_exp_f32_e32 v118, v118
	v_mul_f32_e32 v130, s56, v130
	v_mul_f32_e32 v130, v130, v118
	v_mul_f32_e32 v119, 0x3fb8aa3b, v119
	v_exp_f32_e32 v119, v119
	v_mul_f32_e32 v131, s56, v131
	v_mul_f32_e32 v131, v131, v119
	v_mul_f32_e32 v120, 0x3fb8aa3b, v120
	v_exp_f32_e32 v120, v120
	v_mul_f32_e32 v132, s56, v132
	v_mul_f32_e32 v132, v132, v120
	v_mul_f32_e32 v121, 0x3fb8aa3b, v121
	v_exp_f32_e32 v121, v121
	v_mul_f32_e32 v133, s56, v133
	v_mul_f32_e32 v133, v133, v121
	v_mul_f32_e32 v122, 0x3fb8aa3b, v122
	v_exp_f32_e32 v122, v122
	v_mul_f32_e32 v134, s56, v134
	v_mul_f32_e32 v134, v134, v122
	v_mul_f32_e32 v123, 0x3fb8aa3b, v123
	v_exp_f32_e32 v123, v123
	v_mul_f32_e32 v135, s56, v135
	v_mul_f32_e32 v135, v135, v123
	v_cvt_pk_bf16_f32 v140, v128, v129
	v_cvt_pk_bf16_f32 v141, v130, v131
	v_cvt_pk_bf16_f32 v142, v132, v133
	v_cvt_pk_bf16_f32 v143, v134, v135
	s_lshl_b32 s48, s43, 2
	s_add_u32 s48, s48, 8
	s_add_u32 s48, s48, s41
	s_lshl_b32 s48, s48, 20
	s_lshl_b32 s57, s42, 14
	s_add_u32 s48, s48, s57
	s_add_u32 s48, s48, 8192
	s_add_u32 s58, s92, s48
	s_addc_u32 s59, s93, 0
	s_add_u32 s58, s58, 0x17400000
	s_addc_u32 s59, s59, 0
	global_store_dwordx4 v2, v[140:143], s[58:59] nt
	ds_read_b128 v[116:119], v22 offset:32768
	ds_read_b128 v[120:123], v22 offset:32832
	ds_read_b64 v[124:125], v23 offset:16384
	ds_read_b64 v[126:127], v23 offset:16416
	s_waitcnt lgkmcnt(0)
	v_lshlrev_b32_e32 v128, 16, v124
	v_and_b32_e32 v129, 0xffff0000, v124
	v_lshlrev_b32_e32 v130, 16, v125
	v_and_b32_e32 v131, 0xffff0000, v125
	v_lshlrev_b32_e32 v132, 16, v126
	v_and_b32_e32 v133, 0xffff0000, v126
	v_lshlrev_b32_e32 v134, 16, v127
	v_and_b32_e32 v135, 0xffff0000, v127
	v_mul_f32_e32 v116, 0xbfb8aa3b, v116
	v_exp_f32_e32 v116, v116
	s_nop 0
	v_mul_f32_e32 v128, v116, v128
	v_mul_f32_e32 v117, 0xbfb8aa3b, v117
	v_exp_f32_e32 v117, v117
	s_nop 0
	v_mul_f32_e32 v129, v117, v129
	v_mul_f32_e32 v118, 0xbfb8aa3b, v118
	v_exp_f32_e32 v118, v118
	s_nop 0
	v_mul_f32_e32 v130, v118, v130
	v_mul_f32_e32 v119, 0xbfb8aa3b, v119
	v_exp_f32_e32 v119, v119
	s_nop 0
	v_mul_f32_e32 v131, v119, v131
	v_mul_f32_e32 v120, 0xbfb8aa3b, v120
	v_exp_f32_e32 v120, v120
	s_nop 0
	v_mul_f32_e32 v132, v120, v132
	v_mul_f32_e32 v121, 0xbfb8aa3b, v121
	v_exp_f32_e32 v121, v121
	s_nop 0
	v_mul_f32_e32 v133, v121, v133
	v_mul_f32_e32 v122, 0xbfb8aa3b, v122
	v_exp_f32_e32 v122, v122
	s_nop 0
	v_mul_f32_e32 v134, v122, v134
	v_mul_f32_e32 v123, 0xbfb8aa3b, v123
	v_exp_f32_e32 v123, v123
	s_nop 0
	v_mul_f32_e32 v135, v123, v135
	v_cvt_pk_bf16_f32 v140, v128, v129
	v_cvt_pk_bf16_f32 v141, v130, v131
	v_cvt_pk_bf16_f32 v142, v132, v133
	v_cvt_pk_bf16_f32 v143, v134, v135
	s_lshl_b32 s48, s43, 2
	s_add_u32 s48, s48, 8
	s_add_u32 s48, s48, s41
	s_lshl_b32 s48, s48, 20
	s_lshl_b32 s57, s42, 14
	s_add_u32 s48, s48, s57
	s_add_u32 s48, s48, 0
	s_add_u32 s58, s92, s48
	s_addc_u32 s59, s93, 0
	s_add_u32 s58, s58, 0x18400000
	s_addc_u32 s59, s59, 0
	global_store_dwordx4 v2, v[140:143], s[58:59] nt
	ds_read_b128 v[116:119], v22 offset:49152
	ds_read_b128 v[120:123], v22 offset:49216
	ds_read_b64 v[124:125], v23 offset:24576
	ds_read_b64 v[126:127], v23 offset:24608
	s_waitcnt lgkmcnt(0)
	v_lshlrev_b32_e32 v128, 16, v124
	v_and_b32_e32 v129, 0xffff0000, v124
	v_lshlrev_b32_e32 v130, 16, v125
	v_and_b32_e32 v131, 0xffff0000, v125
	v_lshlrev_b32_e32 v132, 16, v126
	v_and_b32_e32 v133, 0xffff0000, v126
	v_lshlrev_b32_e32 v134, 16, v127
	v_and_b32_e32 v135, 0xffff0000, v127
	v_mul_f32_e32 v116, 0xbfb8aa3b, v116
	v_exp_f32_e32 v116, v116
	s_nop 0
	v_mul_f32_e32 v128, v116, v128
	v_mul_f32_e32 v117, 0xbfb8aa3b, v117
	v_exp_f32_e32 v117, v117
	s_nop 0
	v_mul_f32_e32 v129, v117, v129
	v_mul_f32_e32 v118, 0xbfb8aa3b, v118
	v_exp_f32_e32 v118, v118
	s_nop 0
	v_mul_f32_e32 v130, v118, v130
	v_mul_f32_e32 v119, 0xbfb8aa3b, v119
	v_exp_f32_e32 v119, v119
	s_nop 0
	v_mul_f32_e32 v131, v119, v131
	v_mul_f32_e32 v120, 0xbfb8aa3b, v120
	v_exp_f32_e32 v120, v120
	s_nop 0
	v_mul_f32_e32 v132, v120, v132
	v_mul_f32_e32 v121, 0xbfb8aa3b, v121
	v_exp_f32_e32 v121, v121
	s_nop 0
	v_mul_f32_e32 v133, v121, v133
	v_mul_f32_e32 v122, 0xbfb8aa3b, v122
	v_exp_f32_e32 v122, v122
	s_nop 0
	v_mul_f32_e32 v134, v122, v134
	v_mul_f32_e32 v123, 0xbfb8aa3b, v123
	v_exp_f32_e32 v123, v123
	s_nop 0
	v_mul_f32_e32 v135, v123, v135
	v_cvt_pk_bf16_f32 v140, v128, v129
	v_cvt_pk_bf16_f32 v141, v130, v131
	v_cvt_pk_bf16_f32 v142, v132, v133
	v_cvt_pk_bf16_f32 v143, v134, v135
	s_lshl_b32 s48, s43, 2
	s_add_u32 s48, s48, 8
	s_add_u32 s48, s48, s41
	s_lshl_b32 s48, s48, 20
	s_lshl_b32 s57, s42, 14
	s_add_u32 s48, s48, s57
	s_add_u32 s48, s48, 8192
	s_add_u32 s58, s92, s48
	s_addc_u32 s59, s93, 0
	s_add_u32 s58, s58, 0x18400000
	s_addc_u32 s59, s59, 0
	global_store_dwordx4 v2, v[140:143], s[58:59] nt
	s_branch .Lgl_unit
